# v61 + grid barrier: non-leader workgroups poll the top-level generation word directly (one polling hop fewer)
# speedup vs baseline: 1.0003x; 1.0003x over previous
; __device__ __forceinline__ unsigned xb_ld(GAS unsigned* p)              { return __hip_atomic_load(p, __ATOMIC_RELAXED, __HIP_MEMORY_SCOPE_AGENT); }
; __device__ __forceinline__ unsigned xb_add(GAS unsigned* p, unsigned v) { return __hip_atomic_fetch_add(p, v, __ATOMIC_RELAXED, __HIP_MEMORY_SCOPE_AGENT); }
; #define XB_SPIN(cond, bar) do { unsigned _sp = 0; while (cond) { __builtin_amdgcn_s_sleep(1); \
;     if ((++_sp & 255u) == 0u) { if (xb_ld(&(bar)[XB_TMO])) break; if (_sp > XB_SPIN_CAP) { xb_add(&(bar)[XB_TMO], 1u); break; } } } } while (0)
; __device__ __forceinline__ void xcd_barrier(const XcdBarrier& b, int wave) {
;     ...
;         const unsigned old = xb_add(&bar[XB_XSUB(b.x)], 1u);
;         const unsigned gen = old / nloc;
;         if (old + 1u == (gen + 1u) * nloc) {
;             __builtin_amdgcn_fence(__ATOMIC_RELEASE, "agent");
;             asm volatile("s_waitcnt vmcnt(0)" ::: "memory");
;             const unsigned og = xb_add(&bar[XB_TOP], 1u);
;             const unsigned tg = og / nx;
;             if (og + 1u == (tg + 1u) * nx) xb_add(&bar[XB_TOPGEN], 1u);
;             else XB_SPIN(xb_ld(&bar[XB_TOPGEN]) == tg, bar);
;             __builtin_amdgcn_fence(__ATOMIC_ACQUIRE, "agent");
;             xb_add(&bar[XB_XGEN(b.x)], 1u);
;             asm volatile("s_waitcnt vmcnt(0)" ::: "memory");
;         } else {
;             XB_SPIN(xb_ld(&bar[XB_XGEN(b.x)]) == gen, bar);
;             __builtin_amdgcn_fence(__ATOMIC_ACQUIRE, "agent");
.LBB0_141:
	v_readlane_b32 s12, v243, 47
	v_readlane_b32 s13, v243, 48
	v_cvt_f32_u32_e32 v1, v2
	v_sub_u32_e32 v4, 0, v2
	v_rcp_iflag_f32_e32 v1, v1
	s_nop 1
	global_atomic_add v3, v173, v213, s[12:13] sc0
	v_mul_f32_e32 v1, 0x4f7ffffe, v1
	v_cvt_u32_f32_e32 v1, v1
	v_mul_lo_u32 v4, v4, v1
	v_mul_hi_u32 v4, v1, v4
	v_add_u32_e32 v1, v1, v4
	s_waitcnt vmcnt(0)
	v_mul_hi_u32 v1, v3, v1
	v_mul_lo_u32 v4, v1, v2
	v_sub_u32_e32 v4, v3, v4
	v_add_u32_e32 v5, 1, v1
	v_sub_u32_e32 v6, v4, v2
	v_cmp_ge_u32_e32 vcc, v4, v2
	v_add_u32_e32 v3, 1, v3
	s_nop 0
	v_cndmask_b32_e32 v1, v1, v5, vcc
	v_cndmask_b32_e32 v4, v4, v6, vcc
	v_add_u32_e32 v5, 1, v1
	v_cmp_ge_u32_e32 vcc, v4, v2
	s_nop 1
	v_cndmask_b32_e32 v1, v1, v5, vcc
	v_mul_lo_u32 v4, v2, v1
	v_add_u32_e32 v2, v4, v2
	v_cmp_ne_u32_e32 vcc, v3, v2
	s_and_saveexec_b64 s[12:13], vcc
	s_xor_b64 s[24:25], exec, s[12:13]
	s_cbranch_execz .LBB0_154
	v_readlane_b32 s12, v243, 53
	v_readlane_b32 s13, v243, 54
	s_waitcnt lgkmcnt(0)
	s_nop 3
	global_load_dword v0, v173, s[12:13] sc1
	s_waitcnt vmcnt(0)
	v_cmp_eq_u32_e32 vcc, v0, v1
	s_and_saveexec_b64 s[26:27], vcc
	s_cbranch_execz .LBB0_153
	s_mov_b32 s12, 1
	s_mov_b64 s[34:35], 0
	s_branch .LBB0_145

; __device__ __forceinline__ unsigned xb_ld(GAS unsigned* p)              { return __hip_atomic_load(p, __ATOMIC_RELAXED, __HIP_MEMORY_SCOPE_AGENT); }
; #define XB_SPIN(cond, bar) do { unsigned _sp = 0; while (cond) { __builtin_amdgcn_s_sleep(1); \
;     if ((++_sp & 255u) == 0u) { if (xb_ld(&(bar)[XB_TMO])) break; if (_sp > XB_SPIN_CAP) { xb_add(&(bar)[XB_TMO], 1u); break; } } } } while (0)
; __device__ __forceinline__ void xcd_barrier(const XcdBarrier& b, int wave) {
;     ...
;             XB_SPIN(xb_ld(&bar[XB_XGEN(b.x)]) == gen, bar);
;             __builtin_amdgcn_fence(__ATOMIC_ACQUIRE, "agent");
.LBB0_147:
	v_readlane_b32 s14, v243, 53
	v_readlane_b32 s15, v243, 54
	s_add_i32 s12, s12, 1
	s_mov_b64 s[56:57], -1
	s_nop 2
	global_load_dword v0, v173, s[14:15] sc1
	s_waitcnt vmcnt(0)
	v_cmp_ne_u32_e32 vcc, v0, v1
	s_orn2_b64 s[52:53], vcc, exec
	s_branch .LBB0_144

; __device__ __forceinline__ unsigned xb_ld(GAS unsigned* p)              { return __hip_atomic_load(p, __ATOMIC_RELAXED, __HIP_MEMORY_SCOPE_AGENT); }
; __device__ __forceinline__ unsigned xb_add(GAS unsigned* p, unsigned v) { return __hip_atomic_fetch_add(p, v, __ATOMIC_RELAXED, __HIP_MEMORY_SCOPE_AGENT); }
; #define XB_SPIN(cond, bar) do { unsigned _sp = 0; while (cond) { __builtin_amdgcn_s_sleep(1); \
;     if ((++_sp & 255u) == 0u) { if (xb_ld(&(bar)[XB_TMO])) break; if (_sp > XB_SPIN_CAP) { xb_add(&(bar)[XB_TMO], 1u); break; } } } } while (0)
; __device__ __forceinline__ void xcd_barrier(const XcdBarrier& b, int wave) {
;     ...
;         const unsigned old = xb_add(&bar[XB_XSUB(b.x)], 1u);
;         const unsigned gen = old / nloc;
;         if (old + 1u == (gen + 1u) * nloc) {
;             __builtin_amdgcn_fence(__ATOMIC_RELEASE, "agent");
;             asm volatile("s_waitcnt vmcnt(0)" ::: "memory");
;             const unsigned og = xb_add(&bar[XB_TOP], 1u);
;             const unsigned tg = og / nx;
;             if (og + 1u == (tg + 1u) * nx) xb_add(&bar[XB_TOPGEN], 1u);
;             else XB_SPIN(xb_ld(&bar[XB_TOPGEN]) == tg, bar);
;             __builtin_amdgcn_fence(__ATOMIC_ACQUIRE, "agent");
;             xb_add(&bar[XB_XGEN(b.x)], 1u);
;             asm volatile("s_waitcnt vmcnt(0)" ::: "memory");
;         } else {
;             XB_SPIN(xb_ld(&bar[XB_XGEN(b.x)]) == gen, bar);
;             __builtin_amdgcn_fence(__ATOMIC_ACQUIRE, "agent");
.LBB0_520:
	v_readlane_b32 s14, v243, 47
	v_readlane_b32 s15, v243, 48
	v_cvt_f32_u32_e32 v0, v2
	v_sub_u32_e32 v4, 0, v2
	v_rcp_iflag_f32_e32 v0, v0
	s_nop 1
	global_atomic_add v3, v173, v213, s[14:15] sc0
	v_mul_f32_e32 v0, 0x4f7ffffe, v0
	v_cvt_u32_f32_e32 v0, v0
	v_mul_lo_u32 v4, v4, v0
	v_mul_hi_u32 v4, v0, v4
	v_add_u32_e32 v0, v0, v4
	s_waitcnt vmcnt(0)
	v_mul_hi_u32 v0, v3, v0
	v_mul_lo_u32 v4, v0, v2
	v_sub_u32_e32 v4, v3, v4
	v_add_u32_e32 v5, 1, v0
	v_cmp_ge_u32_e32 vcc, v4, v2
	v_add_u32_e32 v3, 1, v3
	s_nop 0
	v_cndmask_b32_e32 v0, v0, v5, vcc
	v_sub_u32_e32 v5, v4, v2
	v_cndmask_b32_e32 v4, v4, v5, vcc
	v_add_u32_e32 v5, 1, v0
	v_cmp_ge_u32_e32 vcc, v4, v2
	s_nop 1
	v_cndmask_b32_e32 v0, v0, v5, vcc
	v_mul_lo_u32 v4, v2, v0
	v_add_u32_e32 v2, v4, v2
	v_cmp_ne_u32_e32 vcc, v3, v2
	s_and_saveexec_b64 s[14:15], vcc
	s_xor_b64 s[24:25], exec, s[14:15]
	s_cbranch_execz .LBB0_533
	v_readlane_b32 s14, v243, 53
	v_readlane_b32 s15, v243, 54
	s_waitcnt lgkmcnt(0)
	s_nop 3
	global_load_dword v1, v173, s[14:15] sc1
	s_waitcnt vmcnt(0)
	v_cmp_eq_u32_e32 vcc, v1, v0
	s_and_saveexec_b64 s[26:27], vcc
	s_cbranch_execz .LBB0_532
	s_mov_b32 s13, 1
	s_mov_b64 s[34:35], 0
	s_branch .LBB0_524

; __device__ __forceinline__ unsigned xb_ld(GAS unsigned* p)              { return __hip_atomic_load(p, __ATOMIC_RELAXED, __HIP_MEMORY_SCOPE_AGENT); }
; #define XB_SPIN(cond, bar) do { unsigned _sp = 0; while (cond) { __builtin_amdgcn_s_sleep(1); \
;     if ((++_sp & 255u) == 0u) { if (xb_ld(&(bar)[XB_TMO])) break; if (_sp > XB_SPIN_CAP) { xb_add(&(bar)[XB_TMO], 1u); break; } } } } while (0)
; __device__ __forceinline__ void xcd_barrier(const XcdBarrier& b, int wave) {
;     ...
;             XB_SPIN(xb_ld(&bar[XB_XGEN(b.x)]) == gen, bar);
;             __builtin_amdgcn_fence(__ATOMIC_ACQUIRE, "agent");
.LBB0_526:
	v_readlane_b32 s14, v243, 53
	v_readlane_b32 s15, v243, 54
	s_add_i32 s13, s13, 1
	s_mov_b64 s[56:57], -1
	s_nop 2
	global_load_dword v1, v173, s[14:15] sc1
	s_waitcnt vmcnt(0)
	v_cmp_ne_u32_e32 vcc, v1, v0
	s_orn2_b64 s[52:53], vcc, exec
	s_branch .LBB0_523

; __device__ __forceinline__ unsigned xb_ld(GAS unsigned* p)              { return __hip_atomic_load(p, __ATOMIC_RELAXED, __HIP_MEMORY_SCOPE_AGENT); }
; __device__ __forceinline__ unsigned xb_add(GAS unsigned* p, unsigned v) { return __hip_atomic_fetch_add(p, v, __ATOMIC_RELAXED, __HIP_MEMORY_SCOPE_AGENT); }
; #define XB_SPIN(cond, bar) do { unsigned _sp = 0; while (cond) { __builtin_amdgcn_s_sleep(1); \
;     if ((++_sp & 255u) == 0u) { if (xb_ld(&(bar)[XB_TMO])) break; if (_sp > XB_SPIN_CAP) { xb_add(&(bar)[XB_TMO], 1u); break; } } } } while (0)
; __device__ __forceinline__ void xcd_barrier(const XcdBarrier& b, int wave) {
;     ...
;         const unsigned old = xb_add(&bar[XB_XSUB(b.x)], 1u);
;         const unsigned gen = old / nloc;
;         if (old + 1u == (gen + 1u) * nloc) {
;             __builtin_amdgcn_fence(__ATOMIC_RELEASE, "agent");
;             asm volatile("s_waitcnt vmcnt(0)" ::: "memory");
;             const unsigned og = xb_add(&bar[XB_TOP], 1u);
;             const unsigned tg = og / nx;
;             if (og + 1u == (tg + 1u) * nx) xb_add(&bar[XB_TOPGEN], 1u);
;             else XB_SPIN(xb_ld(&bar[XB_TOPGEN]) == tg, bar);
;             __builtin_amdgcn_fence(__ATOMIC_ACQUIRE, "agent");
;             xb_add(&bar[XB_XGEN(b.x)], 1u);
;             asm volatile("s_waitcnt vmcnt(0)" ::: "memory");
;         } else {
;             XB_SPIN(xb_ld(&bar[XB_XGEN(b.x)]) == gen, bar);
;             __builtin_amdgcn_fence(__ATOMIC_ACQUIRE, "agent");
.LBB0_898:
	v_readlane_b32 s12, v243, 47
	v_readlane_b32 s13, v243, 48
	v_cvt_f32_u32_e32 v0, v2
	v_sub_u32_e32 v4, 0, v2
	v_rcp_iflag_f32_e32 v0, v0
	s_nop 1
	global_atomic_add v3, v173, v213, s[12:13] sc0
	v_mul_f32_e32 v0, 0x4f7ffffe, v0
	v_cvt_u32_f32_e32 v0, v0
	v_mul_lo_u32 v4, v4, v0
	v_mul_hi_u32 v4, v0, v4
	v_add_u32_e32 v0, v0, v4
	s_waitcnt vmcnt(0)
	v_mul_hi_u32 v0, v3, v0
	v_mul_lo_u32 v4, v0, v2
	v_sub_u32_e32 v4, v3, v4
	v_add_u32_e32 v5, 1, v0
	v_cmp_ge_u32_e32 vcc, v4, v2
	v_add_u32_e32 v3, 1, v3
	s_nop 0
	v_cndmask_b32_e32 v0, v0, v5, vcc
	v_sub_u32_e32 v5, v4, v2
	v_cndmask_b32_e32 v4, v4, v5, vcc
	v_add_u32_e32 v5, 1, v0
	v_cmp_ge_u32_e32 vcc, v4, v2
	s_nop 1
	v_cndmask_b32_e32 v0, v0, v5, vcc
	v_mul_lo_u32 v4, v2, v0
	v_add_u32_e32 v2, v4, v2
	v_cmp_ne_u32_e32 vcc, v3, v2
	s_and_saveexec_b64 s[12:13], vcc
	s_xor_b64 s[12:13], exec, s[12:13]
	s_cbranch_execz .LBB0_911
	v_readlane_b32 s16, v243, 53
	v_readlane_b32 s17, v243, 54
	s_waitcnt lgkmcnt(0)
	s_nop 3
	global_load_dword v1, v173, s[16:17] sc1
	s_waitcnt vmcnt(0)
	v_cmp_eq_u32_e32 vcc, v1, v0
	s_and_saveexec_b64 s[16:17], vcc
	s_cbranch_execz .LBB0_910
	s_mov_b32 s15, 1
	s_mov_b64 s[24:25], 0
	s_branch .LBB0_902

; __device__ __forceinline__ unsigned xb_ld(GAS unsigned* p)              { return __hip_atomic_load(p, __ATOMIC_RELAXED, __HIP_MEMORY_SCOPE_AGENT); }
; #define XB_SPIN(cond, bar) do { unsigned _sp = 0; while (cond) { __builtin_amdgcn_s_sleep(1); \
;     if ((++_sp & 255u) == 0u) { if (xb_ld(&(bar)[XB_TMO])) break; if (_sp > XB_SPIN_CAP) { xb_add(&(bar)[XB_TMO], 1u); break; } } } } while (0)
; __device__ __forceinline__ void xcd_barrier(const XcdBarrier& b, int wave) {
;     ...
;             XB_SPIN(xb_ld(&bar[XB_XGEN(b.x)]) == gen, bar);
;             __builtin_amdgcn_fence(__ATOMIC_ACQUIRE, "agent");
.LBB0_904:
	v_readlane_b32 s36, v243, 53
	v_readlane_b32 s37, v243, 54
	s_add_i32 s15, s15, 1
	s_mov_b64 s[52:53], -1
	s_nop 2
	global_load_dword v1, v173, s[36:37] sc1
	s_waitcnt vmcnt(0)
	v_cmp_ne_u32_e32 vcc, v1, v0
	s_orn2_b64 s[36:37], vcc, exec
	s_branch .LBB0_901

; __device__ __forceinline__ unsigned xb_ld(GAS unsigned* p)              { return __hip_atomic_load(p, __ATOMIC_RELAXED, __HIP_MEMORY_SCOPE_AGENT); }
; __device__ __forceinline__ unsigned xb_add(GAS unsigned* p, unsigned v) { return __hip_atomic_fetch_add(p, v, __ATOMIC_RELAXED, __HIP_MEMORY_SCOPE_AGENT); }
; #define XB_SPIN(cond, bar) do { unsigned _sp = 0; while (cond) { __builtin_amdgcn_s_sleep(1); \
;     if ((++_sp & 255u) == 0u) { if (xb_ld(&(bar)[XB_TMO])) break; if (_sp > XB_SPIN_CAP) { xb_add(&(bar)[XB_TMO], 1u); break; } } } } while (0)
; __device__ __forceinline__ void xcd_barrier(const XcdBarrier& b, int wave) {
;     ...
;         const unsigned old = xb_add(&bar[XB_XSUB(b.x)], 1u);
;         const unsigned gen = old / nloc;
;         if (old + 1u == (gen + 1u) * nloc) {
;             __builtin_amdgcn_fence(__ATOMIC_RELEASE, "agent");
;             asm volatile("s_waitcnt vmcnt(0)" ::: "memory");
;             const unsigned og = xb_add(&bar[XB_TOP], 1u);
;             const unsigned tg = og / nx;
;             if (og + 1u == (tg + 1u) * nx) xb_add(&bar[XB_TOPGEN], 1u);
;             else XB_SPIN(xb_ld(&bar[XB_TOPGEN]) == tg, bar);
;             __builtin_amdgcn_fence(__ATOMIC_ACQUIRE, "agent");
;             xb_add(&bar[XB_XGEN(b.x)], 1u);
;             asm volatile("s_waitcnt vmcnt(0)" ::: "memory");
;         } else {
;             XB_SPIN(xb_ld(&bar[XB_XGEN(b.x)]) == gen, bar);
;             __builtin_amdgcn_fence(__ATOMIC_ACQUIRE, "agent");
.LBB0_1141:
	v_readlane_b32 s12, v243, 47
	v_readlane_b32 s13, v243, 48
	v_cvt_f32_u32_e32 v0, v2
	v_sub_u32_e32 v4, 0, v2
	v_rcp_iflag_f32_e32 v0, v0
	s_nop 1
	global_atomic_add v3, v173, v213, s[12:13] sc0
	v_mul_f32_e32 v0, 0x4f7ffffe, v0
	v_cvt_u32_f32_e32 v0, v0
	v_mul_lo_u32 v4, v4, v0
	v_mul_hi_u32 v4, v0, v4
	v_add_u32_e32 v0, v0, v4
	s_waitcnt vmcnt(0)
	v_mul_hi_u32 v0, v3, v0
	v_mul_lo_u32 v4, v0, v2
	v_sub_u32_e32 v4, v3, v4
	v_add_u32_e32 v5, 1, v0
	v_cmp_ge_u32_e32 vcc, v4, v2
	v_add_u32_e32 v3, 1, v3
	s_nop 0
	v_cndmask_b32_e32 v0, v0, v5, vcc
	v_sub_u32_e32 v5, v4, v2
	v_cndmask_b32_e32 v4, v4, v5, vcc
	v_add_u32_e32 v5, 1, v0
	v_cmp_ge_u32_e32 vcc, v4, v2
	s_nop 1
	v_cndmask_b32_e32 v0, v0, v5, vcc
	v_mul_lo_u32 v4, v2, v0
	v_add_u32_e32 v2, v4, v2
	v_cmp_ne_u32_e32 vcc, v3, v2
	s_and_saveexec_b64 s[12:13], vcc
	s_xor_b64 s[12:13], exec, s[12:13]
	s_cbranch_execz .LBB0_1154
	v_readlane_b32 s14, v243, 53
	v_readlane_b32 s15, v243, 54
	s_waitcnt lgkmcnt(0)
	s_nop 3
	global_load_dword v1, v173, s[14:15] sc1
	s_waitcnt vmcnt(0)
	v_cmp_eq_u32_e32 vcc, v1, v0
	s_and_saveexec_b64 s[16:17], vcc
	s_cbranch_execz .LBB0_1153
	s_mov_b32 s14, 1
	s_mov_b64 s[24:25], 0
	s_branch .LBB0_1145

; __device__ __forceinline__ unsigned xb_ld(GAS unsigned* p)              { return __hip_atomic_load(p, __ATOMIC_RELAXED, __HIP_MEMORY_SCOPE_AGENT); }
; #define XB_SPIN(cond, bar) do { unsigned _sp = 0; while (cond) { __builtin_amdgcn_s_sleep(1); \
;     if ((++_sp & 255u) == 0u) { if (xb_ld(&(bar)[XB_TMO])) break; if (_sp > XB_SPIN_CAP) { xb_add(&(bar)[XB_TMO], 1u); break; } } } } while (0)
; __device__ __forceinline__ void xcd_barrier(const XcdBarrier& b, int wave) {
;     ...
;             XB_SPIN(xb_ld(&bar[XB_XGEN(b.x)]) == gen, bar);
;             __builtin_amdgcn_fence(__ATOMIC_ACQUIRE, "agent");
.LBB0_1147:
	v_readlane_b32 s36, v243, 53
	v_readlane_b32 s37, v243, 54
	s_add_i32 s14, s14, 1
	s_mov_b64 s[52:53], -1
	s_nop 2
	global_load_dword v1, v173, s[36:37] sc1
	s_waitcnt vmcnt(0)
	v_cmp_ne_u32_e32 vcc, v1, v0
	s_orn2_b64 s[36:37], vcc, exec
	s_branch .LBB0_1144

; __device__ __forceinline__ unsigned xb_ld(GAS unsigned* p)              { return __hip_atomic_load(p, __ATOMIC_RELAXED, __HIP_MEMORY_SCOPE_AGENT); }
; __device__ __forceinline__ unsigned xb_add(GAS unsigned* p, unsigned v) { return __hip_atomic_fetch_add(p, v, __ATOMIC_RELAXED, __HIP_MEMORY_SCOPE_AGENT); }
; #define XB_SPIN(cond, bar) do { unsigned _sp = 0; while (cond) { __builtin_amdgcn_s_sleep(1); \
;     if ((++_sp & 255u) == 0u) { if (xb_ld(&(bar)[XB_TMO])) break; if (_sp > XB_SPIN_CAP) { xb_add(&(bar)[XB_TMO], 1u); break; } } } } while (0)
; __device__ __forceinline__ void xcd_barrier(const XcdBarrier& b, int wave) {
;     ...
;         const unsigned old = xb_add(&bar[XB_XSUB(b.x)], 1u);
;         const unsigned gen = old / nloc;
;         if (old + 1u == (gen + 1u) * nloc) {
;             __builtin_amdgcn_fence(__ATOMIC_RELEASE, "agent");
;             asm volatile("s_waitcnt vmcnt(0)" ::: "memory");
;             const unsigned og = xb_add(&bar[XB_TOP], 1u);
;             const unsigned tg = og / nx;
;             if (og + 1u == (tg + 1u) * nx) xb_add(&bar[XB_TOPGEN], 1u);
;             else XB_SPIN(xb_ld(&bar[XB_TOPGEN]) == tg, bar);
;             __builtin_amdgcn_fence(__ATOMIC_ACQUIRE, "agent");
;             xb_add(&bar[XB_XGEN(b.x)], 1u);
;             asm volatile("s_waitcnt vmcnt(0)" ::: "memory");
;         } else {
;             XB_SPIN(xb_ld(&bar[XB_XGEN(b.x)]) == gen, bar);
;             __builtin_amdgcn_fence(__ATOMIC_ACQUIRE, "agent");
.LBB0_1297:
	v_readlane_b32 s12, v243, 47
	v_readlane_b32 s13, v243, 48
	v_cvt_f32_u32_e32 v0, v2
	v_sub_u32_e32 v4, 0, v2
	v_rcp_iflag_f32_e32 v0, v0
	s_nop 1
	global_atomic_add v3, v173, v213, s[12:13] sc0
	v_mul_f32_e32 v0, 0x4f7ffffe, v0
	v_cvt_u32_f32_e32 v0, v0
	v_mul_lo_u32 v4, v4, v0
	v_mul_hi_u32 v4, v0, v4
	v_add_u32_e32 v0, v0, v4
	s_waitcnt vmcnt(0)
	v_mul_hi_u32 v0, v3, v0
	v_mul_lo_u32 v4, v0, v2
	v_sub_u32_e32 v4, v3, v4
	v_add_u32_e32 v5, 1, v0
	v_cmp_ge_u32_e32 vcc, v4, v2
	v_add_u32_e32 v3, 1, v3
	s_nop 0
	v_cndmask_b32_e32 v0, v0, v5, vcc
	v_sub_u32_e32 v5, v4, v2
	v_cndmask_b32_e32 v4, v4, v5, vcc
	v_add_u32_e32 v5, 1, v0
	v_cmp_ge_u32_e32 vcc, v4, v2
	s_nop 1
	v_cndmask_b32_e32 v0, v0, v5, vcc
	v_mul_lo_u32 v4, v2, v0
	v_add_u32_e32 v2, v4, v2
	v_cmp_ne_u32_e32 vcc, v3, v2
	s_and_saveexec_b64 s[12:13], vcc
	s_xor_b64 s[12:13], exec, s[12:13]
	s_cbranch_execz .LBB0_1310
	v_readlane_b32 s14, v243, 53
	v_readlane_b32 s15, v243, 54
	s_waitcnt lgkmcnt(0)
	s_nop 3
	global_load_dword v1, v173, s[14:15] sc1
	s_waitcnt vmcnt(0)
	v_cmp_eq_u32_e32 vcc, v1, v0
	s_and_saveexec_b64 s[14:15], vcc
	s_cbranch_execz .LBB0_1309
	s_mov_b32 s20, 1
	s_mov_b64 s[16:17], 0
	s_branch .LBB0_1301

; __device__ __forceinline__ unsigned xb_ld(GAS unsigned* p)              { return __hip_atomic_load(p, __ATOMIC_RELAXED, __HIP_MEMORY_SCOPE_AGENT); }
; #define XB_SPIN(cond, bar) do { unsigned _sp = 0; while (cond) { __builtin_amdgcn_s_sleep(1); \
;     if ((++_sp & 255u) == 0u) { if (xb_ld(&(bar)[XB_TMO])) break; if (_sp > XB_SPIN_CAP) { xb_add(&(bar)[XB_TMO], 1u); break; } } } } while (0)
; __device__ __forceinline__ void xcd_barrier(const XcdBarrier& b, int wave) {
;     ...
;             XB_SPIN(xb_ld(&bar[XB_XGEN(b.x)]) == gen, bar);
;             __builtin_amdgcn_fence(__ATOMIC_ACQUIRE, "agent");
.LBB0_1303:
	v_readlane_b32 s26, v243, 53
	v_readlane_b32 s27, v243, 54
	s_add_i32 s20, s20, 1
	s_mov_b64 s[36:37], -1
	s_nop 2
	global_load_dword v1, v173, s[26:27] sc1
	s_waitcnt vmcnt(0)
	v_cmp_ne_u32_e32 vcc, v1, v0
	s_orn2_b64 s[26:27], vcc, exec
	s_branch .LBB0_1300
